# v25 plus one static s_setprio 1 for waves 4-7 at the start of the retention-states phase (persists through retention until the next GEMM phase resets it)
# speedup vs baseline: 1.0021x; 1.0021x over previous
; #define LAS __attribute__((address_space(3)))
; __device__ __forceinline__ void state_unit(LAS unsigned char* lds, const Args& a, int b, int hh, int dir, int eh, int wid, int lane) {
;     unsigned char* ws = a.ws;
;     asm volatile("" : "+v"(lane));
;     const int r = lane & 31, h = lane >> 5, tq = (lane & 15) >> 2, tp = lane & 3, g16 = (lane >> 4) & 1;
;     float lg2 = -log1pf(expf(-(dir ? a.dec_b[hh] : a.dec_f[hh]))) * 1.4426950408889634f;
;     lg2 = __uint_as_float(__builtin_amdgcn_readfirstlane(__float_as_uint(lg2)));
;     const float m = exp2f(dir ? lg2 : -lg2);
;     const float gch = exp2f((float)RCH * lg2);
;     const bf16_t* Kc = (const bf16_t*)(ws + WS_KC) + (size_t)(b * LCTX) * DM + hh * 256; const bf16_t* Vc = (const bf16_t*)(ws + WS_VC) + (size_t)(b * LCTX) * DM + hh * 256;
;     const bf16_t* Kl = (const bf16_t*)(ws + WS_K) + (size_t)(b * SEQ) * DM + hh * 256; const bf16_t* Vl = (const bf16_t*)(ws + WS_V) + (size_t)(b * SEQ) * DM + hh * 256;
;     bf16_t* ST = (bf16_t*)a.out + (size_t)MTOK * DM + (size_t)((b * 8 + hh) * 2 * NRCH) * 65536;
; __global__ void __launch_bounds__(512, 2) fwd_megakernel(Args a) {
;     ...
;     for (int idx = bx; idx < 256; idx += G) { state_unit(lds, a, idx >> 5, (idx >> 2) & 7, (idx >> 1) & 1, idx & 1, wid, lane); __syncthreads(); }
.LBB0_575:
	s_or_b64 exec, exec, s[0:1]
	s_andn2_b64 vcc, exec, s[48:49]
	s_waitcnt lgkmcnt(0)
	s_barrier
	s_cbranch_vccnz .LBB0_595
	s_lshl_b32 s0, s92, 2
	s_or_b32 s1, s0, 1
	s_lshl_b32 s7, s1, 1
	s_lshl_b32 s8, s1, 10
	s_or_b32 s1, s0, 2
	s_or_b32 s0, s0, 3
	s_lshl_b32 s11, s0, 1
	s_lshl_b32 s14, s0, 10
	s_lshl_b32 s0, s92, 1
	s_or_b32 s0, s0, 1
	s_lshl_b32 s22, s0, 2
	s_lshl_b32 s23, s0, 10
	s_and_b32 s0, s97, 0xffffff00
	s_add_i32 s34, s0, 0
	s_lshl_b32 s3, s92, 3
	s_lshl_b32 s6, s92, 12
	s_lshl_b32 s9, s1, 1
	s_lshl_b32 s10, s1, 10
	s_lshl_b32 s15, s92, 11
	s_lshl_b32 s33, s92, 5
	s_add_i32 s35, s34, 0x6800
	s_add_i32 s44, s34, 0x6000
	s_add_i32 s45, s34, 0x4800
	s_add_i32 s52, s34, 0x4000
	s_add_i32 s53, s34, 0x2800
	s_add_i32 s54, s34, 0x2000
	s_add_i32 s55, s34, 0x800
	s_add_u32 s56, s28, 0x1a380000
	s_mov_b32 s41, 0
	s_addc_u32 s57, s29, 0
	v_mov_b32_e32 v69, 0
	v_mov_b32_e32 v71, 0x7f800000
	v_mov_b32_e32 v128, 0x3ecc95a3
	v_mov_b32_e32 v129, 0xbfb8aa3b
	s_mov_b32 s58, 0xc2fc0000
	v_mov_b32_e32 v130, 0x42800000
	v_mov_b32_e32 v131, s6
	v_mov_b32_e32 v132, s8
	v_mov_b32_e32 v133, s10
	v_mov_b32_e32 v134, s14
	v_mov_b32_e32 v135, s15
	s_add_i32 s59, 0, 0x8000
	v_mov_b32_e32 v136, s23
	s_add_i32 s60, 0, 0xc000
	s_add_i32 s61, 0, 0x14000
	s_add_i32 s62, 0, 0xb400
	s_add_i32 s63, 0, 0xb000
	s_add_i32 s64, 0, 0xa400
	s_add_i32 s65, 0, 0xa000
	s_add_i32 s66, 0, 0x9400
	s_add_i32 s67, 0, 0x9000
	s_add_i32 s68, 0, 0x8400
	s_and_b32 s69, s2, 7
	s_lshl_b32 s69, s69, 2
	s_bfe_u32 s98, s2, 0x30003
	s_lshl_b32 s98, s98, 5
	s_or_b32 s69, s69, s98
	s_lshr_b32 s98, s2, 6
	s_or_b32 s69, s69, s98
	s_cmpk_eq_i32 s30, 0x100
	s_cselect_b32 s69, s69, s2
	s_cmp_lt_u32 s92, 4
	s_cbranch_scc1 .Lprio_skip
	s_setprio 1
.Lprio_skip:
	s_branch .LBB0_578
; __device__ __forceinline__ unsigned cvtpk(float lo, float hi) { f32x2 v = {lo, hi}; bf16x2_t b = __builtin_convertvector(v, bf16x2_t); return __builtin_bit_cast(unsigned, b); }
; __device__ __forceinline__ void state_unit(LAS unsigned char* lds, const Args& a, int b, int hh, int dir, int eh, int wid, int lane) {
;     ...
;     { bf16_t* S = ST + (size_t)(dir ? NRCH : NRCH - 1) * 65536;
; #pragma unroll
;       for (int d = 0; d < 4; ++d)
; #pragma unroll
;           for (int i = 0; i < 16; ++i) S[(size_t)(32 * wid + (i & 3) + 8 * (i >> 2) + 4 * h) * 256 + 128 * eh + 32 * d + r] = (bf16_t)(cvtpk(acc[d][i], 0.f) & 0xffffu); }
; __global__ void __launch_bounds__(512, 2) fwd_megakernel(Args a) {
;     ...
;     for (int idx = bx; idx < 256; idx += G) { state_unit(lds, a, idx >> 5, (idx >> 2) & 7, (idx >> 1) & 1, idx & 1, wid, lane); __syncthreads(); }
.LBB0_577:
	s_and_b64 s[0:1], s[0:1], exec
	s_mov_b32 s0, 0x60000
	s_cselect_b32 s0, s0, 0x80000
	s_add_u32 s0, s4, s0
	s_addc_u32 s1, s5, 0
	v_lshlrev_b32_e32 v68, 1, v70
	v_lshl_add_u64 v[64:65], s[0:1], 0, v[68:69]
	s_lshl_b32 s40, s74, 1
	v_lshl_add_u64 v[64:65], v[64:65], 0, s[40:41]
	v_cvt_pk_bf16_f32 v48, v48, s0
	v_lshl_add_u64 v[66:67], v[64:65], 0, v[86:87]
	v_cvt_pk_bf16_f32 v32, v32, s0
	v_cvt_pk_bf16_f32 v16, v16, s0
	v_cvt_pk_bf16_f32 v0, v0, s0
	global_store_short v[66:67], v48, off
	v_cvt_pk_bf16_f32 v68, v49, s0
	v_lshl_add_u64 v[48:49], v[64:65], 0, v[88:89]
	global_store_short v[66:67], v32, off offset:64
	v_cvt_pk_bf16_f32 v32, v33, s0
	global_store_short v[66:67], v16, off offset:128
	v_cvt_pk_bf16_f32 v16, v17, s0
	global_store_short v[66:67], v0, off offset:192
	v_cvt_pk_bf16_f32 v0, v1, s0
	v_cvt_pk_bf16_f32 v50, v50, s0
	v_lshl_add_u64 v[72:73], v[64:65], 0, v[90:91]
	global_store_short v[48:49], v32, off offset:64
	v_cvt_pk_bf16_f32 v32, v34, s0
	global_store_short v[48:49], v16, off offset:128
	v_cvt_pk_bf16_f32 v16, v18, s0
	global_store_short v[48:49], v0, off offset:192
	v_cvt_pk_bf16_f32 v0, v2, s0
	global_store_short v[48:49], v68, off
	global_store_short v[72:73], v50, off
	v_cvt_pk_bf16_f32 v68, v51, s0
	v_lshl_add_u64 v[50:51], v[64:65], 0, v[92:93]
	global_store_short v[72:73], v32, off offset:64
	v_cvt_pk_bf16_f32 v32, v35, s0
	global_store_short v[72:73], v16, off offset:128
	v_cvt_pk_bf16_f32 v16, v19, s0
	global_store_short v[72:73], v0, off offset:192
	v_cvt_pk_bf16_f32 v0, v3, s0
	v_cvt_pk_bf16_f32 v52, v52, s0
	v_lshl_add_u64 v[74:75], v[64:65], 0, v[94:95]
	global_store_short v[50:51], v32, off offset:64
	v_cvt_pk_bf16_f32 v32, v36, s0
	global_store_short v[50:51], v16, off offset:128
	v_cvt_pk_bf16_f32 v16, v20, s0
	global_store_short v[50:51], v0, off offset:192
	v_cvt_pk_bf16_f32 v0, v4, s0
	global_store_short v[50:51], v68, off
	global_store_short v[74:75], v52, off
	v_cvt_pk_bf16_f32 v68, v53, s0
	v_lshl_add_u64 v[52:53], v[64:65], 0, v[98:99]
	global_store_short v[74:75], v32, off offset:64
	v_cvt_pk_bf16_f32 v32, v37, s0
	global_store_short v[74:75], v16, off offset:128
	v_cvt_pk_bf16_f32 v16, v21, s0
	global_store_short v[74:75], v0, off offset:192
	v_cvt_pk_bf16_f32 v0, v5, s0
	v_cvt_pk_bf16_f32 v54, v54, s0
	v_lshl_add_u64 v[76:77], v[64:65], 0, v[100:101]
	global_store_short v[52:53], v32, off offset:64
	v_cvt_pk_bf16_f32 v32, v38, s0
	global_store_short v[52:53], v16, off offset:128
	v_cvt_pk_bf16_f32 v16, v22, s0
	global_store_short v[52:53], v0, off offset:192
	v_cvt_pk_bf16_f32 v0, v6, s0
	global_store_short v[52:53], v68, off
	global_store_short v[76:77], v54, off
	v_cvt_pk_bf16_f32 v68, v55, s0
	v_lshl_add_u64 v[54:55], v[64:65], 0, v[102:103]
	global_store_short v[76:77], v32, off offset:64
	v_cvt_pk_bf16_f32 v32, v39, s0
	global_store_short v[76:77], v16, off offset:128
	v_cvt_pk_bf16_f32 v16, v23, s0
	global_store_short v[76:77], v0, off offset:192
	v_cvt_pk_bf16_f32 v0, v7, s0
	v_cvt_pk_bf16_f32 v56, v56, s0
	v_lshl_add_u64 v[78:79], v[64:65], 0, v[104:105]
	global_store_short v[54:55], v32, off offset:64
	v_cvt_pk_bf16_f32 v32, v40, s0
	global_store_short v[54:55], v16, off offset:128
	v_cvt_pk_bf16_f32 v16, v24, s0
	global_store_short v[54:55], v0, off offset:192
	v_cvt_pk_bf16_f32 v0, v8, s0
	global_store_short v[54:55], v68, off
	global_store_short v[78:79], v56, off
	v_cvt_pk_bf16_f32 v68, v57, s0
	v_lshl_add_u64 v[56:57], v[64:65], 0, v[106:107]
	global_store_short v[78:79], v32, off offset:64
	v_cvt_pk_bf16_f32 v32, v41, s0
	global_store_short v[78:79], v16, off offset:128
	v_cvt_pk_bf16_f32 v16, v25, s0
	global_store_short v[78:79], v0, off offset:192
	v_cvt_pk_bf16_f32 v0, v9, s0
	v_cvt_pk_bf16_f32 v58, v58, s0
	v_lshl_add_u64 v[80:81], v[64:65], 0, v[108:109]
	global_store_short v[56:57], v32, off offset:64
	v_cvt_pk_bf16_f32 v32, v42, s0
	global_store_short v[56:57], v16, off offset:128
	v_cvt_pk_bf16_f32 v16, v26, s0
	global_store_short v[56:57], v0, off offset:192
	v_cvt_pk_bf16_f32 v0, v10, s0
	global_store_short v[56:57], v68, off
	global_store_short v[80:81], v58, off
	v_cvt_pk_bf16_f32 v68, v59, s0
	v_lshl_add_u64 v[58:59], v[64:65], 0, v[110:111]
	global_store_short v[80:81], v32, off offset:64
	v_cvt_pk_bf16_f32 v32, v43, s0
	global_store_short v[80:81], v16, off offset:128
	v_cvt_pk_bf16_f32 v16, v27, s0
	global_store_short v[80:81], v0, off offset:192
	v_cvt_pk_bf16_f32 v0, v11, s0
	v_cvt_pk_bf16_f32 v60, v60, s0
	v_lshl_add_u64 v[82:83], v[64:65], 0, v[112:113]
	global_store_short v[58:59], v32, off offset:64
	v_cvt_pk_bf16_f32 v32, v44, s0
	global_store_short v[58:59], v16, off offset:128
	v_cvt_pk_bf16_f32 v16, v28, s0
	global_store_short v[58:59], v0, off offset:192
	v_cvt_pk_bf16_f32 v0, v12, s0
	global_store_short v[58:59], v68, off
	global_store_short v[82:83], v60, off
	v_cvt_pk_bf16_f32 v68, v61, s0
	v_lshl_add_u64 v[60:61], v[64:65], 0, v[114:115]
	global_store_short v[82:83], v32, off offset:64
	v_cvt_pk_bf16_f32 v32, v45, s0
	global_store_short v[82:83], v16, off offset:128
	v_cvt_pk_bf16_f32 v16, v29, s0
	global_store_short v[82:83], v0, off offset:192
	v_cvt_pk_bf16_f32 v0, v13, s0
	v_cvt_pk_bf16_f32 v62, v62, s0
	v_lshl_add_u64 v[84:85], v[64:65], 0, v[116:117]
	global_store_short v[60:61], v32, off offset:64
	v_cvt_pk_bf16_f32 v32, v46, s0
	global_store_short v[60:61], v16, off offset:128
	v_cvt_pk_bf16_f32 v16, v30, s0
	global_store_short v[60:61], v0, off offset:192
	v_cvt_pk_bf16_f32 v0, v14, s0
	s_add_i32 s69, s69, s30
	global_store_short v[60:61], v68, off
	global_store_short v[84:85], v62, off
	v_cvt_pk_bf16_f32 v68, v63, s0
	v_lshl_add_u64 v[62:63], v[64:65], 0, v[118:119]
	global_store_short v[84:85], v32, off offset:64
	v_cvt_pk_bf16_f32 v32, v47, s0
	global_store_short v[84:85], v16, off offset:128
	v_cvt_pk_bf16_f32 v16, v31, s0
	global_store_short v[84:85], v0, off offset:192
	v_cvt_pk_bf16_f32 v0, v15, s0
	s_cmpk_gt_i32 s69, 0xff
	global_store_short v[62:63], v68, off
	global_store_short v[62:63], v32, off offset:64
	global_store_short v[62:63], v16, off offset:128
	global_store_short v[62:63], v0, off offset:192
	s_waitcnt vmcnt(63) expcnt(7) lgkmcnt(15)
	s_barrier
	s_cbranch_scc1 .LBB0_595
